# accumulator zeroing with 64-bit moves on top of the 4-phase K-loop
# baseline (speedup 1.0000x reference)
;     __host__ __device__ bool next(int i, Unit& u) const { const int j = i / 3; if (!StaticOrder::next(j, u)) return false; u.br = i - 3 * j; return true; }
; template <class Epi, class Sched>
; __device__ __forceinline__ void gemm_phase(PG8_LAS unsigned char* lds, const Gemm g, const Sched& S, const Epi& E) {
;     ...
;         const bool has_next = S.next(ui + 1, nxt);
;         const char* nA = has_next ? (const char*)g.A + (size_t)nxt.pm * tstep + (size_t)nxt.br * g.strideA : cA; const char* nB = has_next ? (const char*)g.Bt + (size_t)nxt.pn * tstepB + (size_t)nxt.br * g.strideB : cB;
;     ...
; #pragma unroll
;         for (int a = 0; a < 2; ++a)
; #pragma unroll
;             for (int b = 0; b < 2; ++b)
; #pragma unroll
;                 for (int m = 0; m < 4; ++m)
; #pragma unroll
;                     for (int n = 0; n < 2; ++n) acc[a][b][m][n] = (f32x4){0.f, 0.f, 0.f, 0.f};
.LBB0_78:
	s_ashr_i32 s13, s12, 31
	v_cmp_lt_i64_e32 vcc, s[16:17], v[140:141]
	s_lshl_b64 s[16:17], s[12:13], 20
	s_add_u32 s16, s31, s16
	s_addc_u32 s17, s36, s17
	s_and_b64 s[18:19], vcc, exec
	s_cselect_b32 s13, s17, s25
	s_cselect_b32 s57, s16, s24
	s_ashr_i32 s15, s14, 31
	s_lshl_b64 s[18:19], s[14:15], 20
	s_add_u32 s18, s6, s18
	s_addc_u32 s19, s7, s19
	s_and_b64 s[26:27], vcc, exec
	s_cselect_b32 s15, s19, s23
	s_cselect_b32 s58, s18, s22
	s_add_u32 s59, s22, 0x10000
	s_addc_u32 s60, s23, 0
	s_add_u32 s22, s24, 0x80080
	v_mov_b32_e32 v0, 0
	s_addc_u32 s23, s25, 0
	s_mov_b32 s61, -2
	v_mov_b32_e32 v1, v0
	v_mov_b64_e32 v[2:3], 0
	v_mov_b64_e32 v[4:5], 0
	v_mov_b64_e32 v[6:7], 0
	v_mov_b64_e32 v[8:9], 0
	v_mov_b64_e32 v[10:11], 0
	v_mov_b64_e32 v[12:13], 0
	v_mov_b64_e32 v[14:15], 0
	v_mov_b64_e32 v[16:17], 0
	v_mov_b64_e32 v[18:19], 0
	v_mov_b64_e32 v[20:21], 0
	v_mov_b64_e32 v[22:23], 0
	v_mov_b64_e32 v[24:25], 0
	v_mov_b64_e32 v[26:27], 0
	v_mov_b64_e32 v[28:29], 0
	v_mov_b64_e32 v[30:31], 0
	v_mov_b64_e32 v[32:33], 0
	v_mov_b64_e32 v[34:35], 0
	v_mov_b64_e32 v[36:37], 0
	v_mov_b64_e32 v[38:39], 0
	v_mov_b64_e32 v[40:41], 0
	v_mov_b64_e32 v[42:43], 0
	v_mov_b64_e32 v[44:45], 0
	v_mov_b64_e32 v[46:47], 0
	v_mov_b64_e32 v[48:49], 0
	v_mov_b64_e32 v[50:51], 0
	v_mov_b64_e32 v[52:53], 0
	v_mov_b64_e32 v[54:55], 0
	v_mov_b64_e32 v[56:57], 0
	v_mov_b64_e32 v[58:59], 0
	v_mov_b64_e32 v[60:61], 0
	v_mov_b64_e32 v[62:63], 0
	v_mov_b64_e32 v[64:65], 0
	v_mov_b64_e32 v[66:67], 0
	v_mov_b64_e32 v[68:69], 0
	v_mov_b64_e32 v[70:71], 0
	v_mov_b64_e32 v[72:73], 0
	v_mov_b64_e32 v[74:75], 0
	v_mov_b64_e32 v[76:77], 0
	v_mov_b64_e32 v[78:79], 0
	v_mov_b64_e32 v[80:81], 0
	v_mov_b64_e32 v[82:83], 0
	v_mov_b64_e32 v[84:85], 0
	v_mov_b64_e32 v[86:87], 0
	v_mov_b64_e32 v[88:89], 0
	v_mov_b64_e32 v[90:91], 0
	v_mov_b64_e32 v[92:93], 0
	v_mov_b64_e32 v[94:95], 0
	v_mov_b64_e32 v[96:97], 0
	v_mov_b64_e32 v[98:99], 0
	v_mov_b64_e32 v[100:101], 0
	v_mov_b64_e32 v[102:103], 0
	v_mov_b64_e32 v[104:105], 0
	v_mov_b64_e32 v[106:107], 0
	v_mov_b64_e32 v[108:109], 0
	v_mov_b64_e32 v[110:111], 0
	v_mov_b64_e32 v[112:113], 0
	v_mov_b64_e32 v[114:115], 0
	v_mov_b64_e32 v[116:117], 0
	v_mov_b64_e32 v[118:119], 0
	v_mov_b64_e32 v[120:121], 0
	v_mov_b64_e32 v[122:123], 0
	v_mov_b64_e32 v[124:125], 0
	v_mov_b64_e32 v[126:127], 0
	s_cmp_eq_u32 s78, 1
	s_cbranch_scc0 .Lhalf_skip_y_0
	s_barrier

; template <class Epi, class Sched>
; __device__ __forceinline__ void gemm_phase(PG8_LAS unsigned char* lds, const Gemm g, const Sched& S, const Epi& E) {
;     ...
; #pragma unroll
;         for (int a = 0; a < 2; ++a)
; #pragma unroll
;             for (int b = 0; b < 2; ++b)
; #pragma unroll
;                 for (int m = 0; m < 4; ++m)
; #pragma unroll
;                     for (int n = 0; n < 2; ++n) acc[a][b][m][n] = (f32x4){0.f, 0.f, 0.f, 0.f};
.LBB0_154:
	s_add_u32 s65, s26, 0x10000
	v_mov_b32_e32 v0, 0
	s_addc_u32 s66, s27, 0
	s_mov_b32 s67, -2
	v_mov_b32_e32 v1, v0
	v_mov_b64_e32 v[2:3], 0
	v_mov_b64_e32 v[4:5], 0
	v_mov_b64_e32 v[6:7], 0
	v_mov_b64_e32 v[8:9], 0
	v_mov_b64_e32 v[10:11], 0
	v_mov_b64_e32 v[12:13], 0
	v_mov_b64_e32 v[14:15], 0
	v_mov_b64_e32 v[16:17], 0
	v_mov_b64_e32 v[18:19], 0
	v_mov_b64_e32 v[20:21], 0
	v_mov_b64_e32 v[22:23], 0
	v_mov_b64_e32 v[24:25], 0
	v_mov_b64_e32 v[26:27], 0
	v_mov_b64_e32 v[28:29], 0
	v_mov_b64_e32 v[30:31], 0
	v_mov_b64_e32 v[32:33], 0
	v_mov_b64_e32 v[34:35], 0
	v_mov_b64_e32 v[36:37], 0
	v_mov_b64_e32 v[38:39], 0
	v_mov_b64_e32 v[40:41], 0
	v_mov_b64_e32 v[42:43], 0
	v_mov_b64_e32 v[44:45], 0
	v_mov_b64_e32 v[46:47], 0
	v_mov_b64_e32 v[48:49], 0
	v_mov_b64_e32 v[50:51], 0
	v_mov_b64_e32 v[52:53], 0
	v_mov_b64_e32 v[54:55], 0
	v_mov_b64_e32 v[56:57], 0
	v_mov_b64_e32 v[58:59], 0
	v_mov_b64_e32 v[60:61], 0
	v_mov_b64_e32 v[62:63], 0
	v_mov_b64_e32 v[64:65], 0
	v_mov_b64_e32 v[66:67], 0
	v_mov_b64_e32 v[68:69], 0
	v_mov_b64_e32 v[70:71], 0
	v_mov_b64_e32 v[72:73], 0
	v_mov_b64_e32 v[74:75], 0
	v_mov_b64_e32 v[76:77], 0
	v_mov_b64_e32 v[78:79], 0
	v_mov_b64_e32 v[80:81], 0
	v_mov_b64_e32 v[82:83], 0
	v_mov_b64_e32 v[84:85], 0
	v_mov_b64_e32 v[86:87], 0
	v_mov_b64_e32 v[88:89], 0
	v_mov_b64_e32 v[90:91], 0
	v_mov_b64_e32 v[92:93], 0
	v_mov_b64_e32 v[94:95], 0
	v_mov_b64_e32 v[96:97], 0
	v_mov_b64_e32 v[98:99], 0
	v_mov_b64_e32 v[100:101], 0
	v_mov_b64_e32 v[102:103], 0
	v_mov_b64_e32 v[104:105], 0
	v_mov_b64_e32 v[106:107], 0
	v_mov_b64_e32 v[108:109], 0
	v_mov_b64_e32 v[110:111], 0
	v_mov_b64_e32 v[112:113], 0
	v_mov_b64_e32 v[114:115], 0
	v_mov_b64_e32 v[116:117], 0
	v_mov_b64_e32 v[118:119], 0
	v_mov_b64_e32 v[120:121], 0
	v_mov_b64_e32 v[122:123], 0
	v_mov_b64_e32 v[124:125], 0
	v_mov_b64_e32 v[126:127], 0
	s_cmp_eq_u32 s78, 1
	s_cbranch_scc0 .Lhalf_skip_y_1
	s_barrier

;     __host__ __device__ bool next(int i, Unit& u) const { const int j = i / 3; if (!StaticOrder::next(j, u)) return false; u.br = i - 3 * j; return true; }
; template <class Epi, class Sched>
; __device__ __forceinline__ void gemm_phase(PG8_LAS unsigned char* lds, const Gemm g, const Sched& S, const Epi& E) {
;     ...
;         const bool has_next = S.next(ui + 1, nxt);
;         const char* nA = has_next ? (const char*)g.A + (size_t)nxt.pm * tstep + (size_t)nxt.br * g.strideA : cA; const char* nB = has_next ? (const char*)g.Bt + (size_t)nxt.pn * tstepB + (size_t)nxt.br * g.strideB : cB;
;     ...
; #pragma unroll
;         for (int a = 0; a < 2; ++a)
; #pragma unroll
;             for (int b = 0; b < 2; ++b)
; #pragma unroll
;                 for (int m = 0; m < 4; ++m)
; #pragma unroll
;                     for (int n = 0; n < 2; ++n) acc[a][b][m][n] = (f32x4){0.f, 0.f, 0.f, 0.f};
.LBB0_279:
	s_ashr_i32 s29, s28, 31
	v_cmp_lt_i64_e32 vcc, s[36:37], v[140:141]
	s_lshl_b64 s[36:37], s[28:29], 20
	s_add_u32 s36, s21, s36
	s_addc_u32 s37, s23, s37
	s_and_b64 s[38:39], vcc, exec
	s_cselect_b32 s9, s37, s49
	s_cselect_b32 s29, s36, s48
	s_ashr_i32 s31, s30, 31
	s_lshl_b64 s[38:39], s[30:31], 20
	s_add_u32 s38, s25, s38
	s_addc_u32 s39, s27, s39
	s_and_b64 s[50:51], vcc, exec
	s_cselect_b32 s31, s39, s7
	s_cselect_b32 s47, s38, s6
	s_add_u32 s67, s6, 0x10000
	s_addc_u32 s68, s7, 0
	s_add_u32 s6, s48, 0x80080
	v_mov_b32_e32 v0, 0
	s_addc_u32 s7, s49, 0
	s_mov_b32 s69, -2
	v_mov_b32_e32 v1, v0
	v_mov_b64_e32 v[2:3], 0
	v_mov_b64_e32 v[4:5], 0
	v_mov_b64_e32 v[6:7], 0
	v_mov_b64_e32 v[8:9], 0
	v_mov_b64_e32 v[10:11], 0
	v_mov_b64_e32 v[12:13], 0
	v_mov_b64_e32 v[14:15], 0
	v_mov_b64_e32 v[16:17], 0
	v_mov_b64_e32 v[18:19], 0
	v_mov_b64_e32 v[20:21], 0
	v_mov_b64_e32 v[22:23], 0
	v_mov_b64_e32 v[24:25], 0
	v_mov_b64_e32 v[26:27], 0
	v_mov_b64_e32 v[28:29], 0
	v_mov_b64_e32 v[30:31], 0
	v_mov_b64_e32 v[32:33], 0
	v_mov_b64_e32 v[34:35], 0
	v_mov_b64_e32 v[36:37], 0
	v_mov_b64_e32 v[38:39], 0
	v_mov_b64_e32 v[40:41], 0
	v_mov_b64_e32 v[42:43], 0
	v_mov_b64_e32 v[44:45], 0
	v_mov_b64_e32 v[46:47], 0
	v_mov_b64_e32 v[48:49], 0
	v_mov_b64_e32 v[50:51], 0
	v_mov_b64_e32 v[52:53], 0
	v_mov_b64_e32 v[54:55], 0
	v_mov_b64_e32 v[56:57], 0
	v_mov_b64_e32 v[58:59], 0
	v_mov_b64_e32 v[60:61], 0
	v_mov_b64_e32 v[62:63], 0
	v_mov_b64_e32 v[64:65], 0
	v_mov_b64_e32 v[66:67], 0
	v_mov_b64_e32 v[68:69], 0
	v_mov_b64_e32 v[70:71], 0
	v_mov_b64_e32 v[72:73], 0
	v_mov_b64_e32 v[74:75], 0
	v_mov_b64_e32 v[76:77], 0
	v_mov_b64_e32 v[78:79], 0
	v_mov_b64_e32 v[80:81], 0
	v_mov_b64_e32 v[82:83], 0
	v_mov_b64_e32 v[84:85], 0
	v_mov_b64_e32 v[86:87], 0
	v_mov_b64_e32 v[88:89], 0
	v_mov_b64_e32 v[90:91], 0
	v_mov_b64_e32 v[92:93], 0
	v_mov_b64_e32 v[94:95], 0
	v_mov_b64_e32 v[96:97], 0
	v_mov_b64_e32 v[98:99], 0
	v_mov_b64_e32 v[100:101], 0
	v_mov_b64_e32 v[102:103], 0
	v_mov_b64_e32 v[104:105], 0
	v_mov_b64_e32 v[106:107], 0
	v_mov_b64_e32 v[108:109], 0
	v_mov_b64_e32 v[110:111], 0
	v_mov_b64_e32 v[112:113], 0
	v_mov_b64_e32 v[114:115], 0
	v_mov_b64_e32 v[116:117], 0
	v_mov_b64_e32 v[118:119], 0
	v_mov_b64_e32 v[120:121], 0
	v_mov_b64_e32 v[122:123], 0
	v_mov_b64_e32 v[124:125], 0
	v_mov_b64_e32 v[126:127], 0
	s_cmp_eq_u32 s78, 1
	s_cbranch_scc0 .Lhalf_skip_y_2
	s_barrier

;     __host__ __device__ bool next(int i, Unit& u) const { const int j = i / 3; if (!StaticOrder::next(j, u)) return false; u.br = i - 3 * j; return true; }
; template <class Epi, class Sched>
; __device__ __forceinline__ void gemm_phase(PG8_LAS unsigned char* lds, const Gemm g, const Sched& S, const Epi& E) {
;     ...
;         const bool has_next = S.next(ui + 1, nxt);
;         const char* nA = has_next ? (const char*)g.A + (size_t)nxt.pm * tstep + (size_t)nxt.br * g.strideA : cA; const char* nB = has_next ? (const char*)g.Bt + (size_t)nxt.pn * tstepB + (size_t)nxt.br * g.strideB : cB;
;     ...
; #pragma unroll
;         for (int a = 0; a < 2; ++a)
; #pragma unroll
;             for (int b = 0; b < 2; ++b)
; #pragma unroll
;                 for (int m = 0; m < 4; ++m)
; #pragma unroll
;                     for (int n = 0; n < 2; ++n) acc[a][b][m][n] = (f32x4){0.f, 0.f, 0.f, 0.f};
.LBB0_396:
	s_ashr_i32 s15, s14, 31
	v_cmp_lt_i64_e64 s[28:29], s[18:19], 32
	s_lshl_b64 s[18:19], s[14:15], 20
	s_add_u32 s18, s46, s18
	s_addc_u32 s19, s47, s19
	s_and_b64 s[20:21], s[28:29], exec
	s_cselect_b32 s5, s19, s27
	s_cselect_b32 s15, s18, s26
	s_ashr_i32 s17, s16, 31
	s_lshl_b64 s[20:21], s[16:17], 20
	s_add_u32 s20, s37, s20
	s_addc_u32 s21, s38, s21
	s_and_b64 s[28:29], s[28:29], exec
	s_cselect_b32 s17, s21, s25
	s_cselect_b32 s23, s20, s24
	s_add_u32 s64, s24, 0x10000
	s_addc_u32 s65, s25, 0
	s_add_u32 s24, s26, 0x80080
	v_mov_b32_e32 v0, 0
	s_addc_u32 s25, s27, 0
	s_mov_b32 s66, -2
	v_mov_b32_e32 v1, v0
	v_mov_b64_e32 v[2:3], 0
	v_mov_b64_e32 v[4:5], 0
	v_mov_b64_e32 v[6:7], 0
	v_mov_b64_e32 v[8:9], 0
	v_mov_b64_e32 v[10:11], 0
	v_mov_b64_e32 v[12:13], 0
	v_mov_b64_e32 v[14:15], 0
	v_mov_b64_e32 v[16:17], 0
	v_mov_b64_e32 v[18:19], 0
	v_mov_b64_e32 v[20:21], 0
	v_mov_b64_e32 v[22:23], 0
	v_mov_b64_e32 v[24:25], 0
	v_mov_b64_e32 v[26:27], 0
	v_mov_b64_e32 v[28:29], 0
	v_mov_b64_e32 v[30:31], 0
	v_mov_b64_e32 v[32:33], 0
	v_mov_b64_e32 v[34:35], 0
	v_mov_b64_e32 v[36:37], 0
	v_mov_b64_e32 v[38:39], 0
	v_mov_b64_e32 v[40:41], 0
	v_mov_b64_e32 v[42:43], 0
	v_mov_b64_e32 v[44:45], 0
	v_mov_b64_e32 v[46:47], 0
	v_mov_b64_e32 v[48:49], 0
	v_mov_b64_e32 v[50:51], 0
	v_mov_b64_e32 v[52:53], 0
	v_mov_b64_e32 v[54:55], 0
	v_mov_b64_e32 v[56:57], 0
	v_mov_b64_e32 v[58:59], 0
	v_mov_b64_e32 v[60:61], 0
	v_mov_b64_e32 v[62:63], 0
	v_mov_b64_e32 v[64:65], 0
	v_mov_b64_e32 v[66:67], 0
	v_mov_b64_e32 v[68:69], 0
	v_mov_b64_e32 v[70:71], 0
	v_mov_b64_e32 v[72:73], 0
	v_mov_b64_e32 v[74:75], 0
	v_mov_b64_e32 v[76:77], 0
	v_mov_b64_e32 v[78:79], 0
	v_mov_b64_e32 v[80:81], 0
	v_mov_b64_e32 v[82:83], 0
	v_mov_b64_e32 v[84:85], 0
	v_mov_b64_e32 v[86:87], 0
	v_mov_b64_e32 v[88:89], 0
	v_mov_b64_e32 v[90:91], 0
	v_mov_b64_e32 v[92:93], 0
	v_mov_b64_e32 v[94:95], 0
	v_mov_b64_e32 v[96:97], 0
	v_mov_b64_e32 v[98:99], 0
	v_mov_b64_e32 v[100:101], 0
	v_mov_b64_e32 v[102:103], 0
	v_mov_b64_e32 v[104:105], 0
	v_mov_b64_e32 v[106:107], 0
	v_mov_b64_e32 v[108:109], 0
	v_mov_b64_e32 v[110:111], 0
	v_mov_b64_e32 v[112:113], 0
	v_mov_b64_e32 v[114:115], 0
	v_mov_b64_e32 v[116:117], 0
	v_mov_b64_e32 v[118:119], 0
	v_mov_b64_e32 v[120:121], 0
	v_mov_b64_e32 v[122:123], 0
	v_mov_b64_e32 v[124:125], 0
	v_mov_b64_e32 v[126:127], 0
	s_cmp_eq_u32 s78, 1
	s_cbranch_scc0 .Lhalf_skip_y_3
	s_barrier

;     __host__ __device__ bool next(int i, Unit& u) const { const int j = i / 3; if (!StaticOrder::next(j, u)) return false; u.br = i - 3 * j; return true; }
; template <class Epi, class Sched>
; __device__ __forceinline__ void gemm_phase(PG8_LAS unsigned char* lds, const Gemm g, const Sched& S, const Epi& E) {
;     ...
;         const bool has_next = S.next(ui + 1, nxt);
;         const char* nA = has_next ? (const char*)g.A + (size_t)nxt.pm * tstep + (size_t)nxt.br * g.strideA : cA; const char* nB = has_next ? (const char*)g.Bt + (size_t)nxt.pn * tstepB + (size_t)nxt.br * g.strideB : cB;
;     ...
; #pragma unroll
;         for (int a = 0; a < 2; ++a)
; #pragma unroll
;             for (int b = 0; b < 2; ++b)
; #pragma unroll
;                 for (int m = 0; m < 4; ++m)
; #pragma unroll
;                     for (int n = 0; n < 2; ++n) acc[a][b][m][n] = (f32x4){0.f, 0.f, 0.f, 0.f};
.LBB0_782:
	s_ashr_i32 s19, s18, 31
	v_cmp_lt_i64_e32 vcc, s[22:23], v[176:177]
	s_lshl_b64 s[22:23], s[18:19], 20
	s_add_u32 s22, s50, s22
	s_addc_u32 s23, s51, s23
	s_and_b64 s[24:25], vcc, exec
	s_cselect_b32 s19, s23, s29
	s_cselect_b32 s65, s22, s28
	s_ashr_i32 s21, s20, 31
	s_lshl_b64 s[24:25], s[20:21], 20
	s_add_u32 s24, s52, s24
	s_addc_u32 s25, s53, s25
	s_and_b64 s[36:37], vcc, exec
	s_cselect_b32 s21, s25, s31
	s_cselect_b32 s66, s24, s30
	s_add_u32 s67, s30, 0x10000
	v_mov_b32_e32 v0, 0
	s_addc_u32 s68, s31, 0
	s_mov_b32 s69, -2
	v_mov_b32_e32 v1, v0
	v_mov_b64_e32 v[2:3], 0
	v_mov_b64_e32 v[4:5], 0
	v_mov_b64_e32 v[6:7], 0
	v_mov_b64_e32 v[8:9], 0
	v_mov_b64_e32 v[10:11], 0
	v_mov_b64_e32 v[12:13], 0
	v_mov_b64_e32 v[14:15], 0
	v_mov_b64_e32 v[16:17], 0
	v_mov_b64_e32 v[18:19], 0
	v_mov_b64_e32 v[20:21], 0
	v_mov_b64_e32 v[22:23], 0
	v_mov_b64_e32 v[24:25], 0
	v_mov_b64_e32 v[26:27], 0
	v_mov_b64_e32 v[28:29], 0
	v_mov_b64_e32 v[30:31], 0
	v_mov_b64_e32 v[32:33], 0
	v_mov_b64_e32 v[34:35], 0
	v_mov_b64_e32 v[36:37], 0
	v_mov_b64_e32 v[38:39], 0
	v_mov_b64_e32 v[40:41], 0
	v_mov_b64_e32 v[42:43], 0
	v_mov_b64_e32 v[44:45], 0
	v_mov_b64_e32 v[46:47], 0
	v_mov_b64_e32 v[48:49], 0
	v_mov_b64_e32 v[50:51], 0
	v_mov_b64_e32 v[52:53], 0
	v_mov_b64_e32 v[54:55], 0
	v_mov_b64_e32 v[56:57], 0
	v_mov_b64_e32 v[58:59], 0
	v_mov_b64_e32 v[60:61], 0
	v_mov_b64_e32 v[62:63], 0
	v_mov_b64_e32 v[64:65], 0
	v_mov_b64_e32 v[66:67], 0
	v_mov_b64_e32 v[68:69], 0
	v_mov_b64_e32 v[70:71], 0
	v_mov_b64_e32 v[72:73], 0
	v_mov_b64_e32 v[74:75], 0
	v_mov_b64_e32 v[76:77], 0
	v_mov_b64_e32 v[78:79], 0
	v_mov_b64_e32 v[80:81], 0
	v_mov_b64_e32 v[82:83], 0
	v_mov_b64_e32 v[84:85], 0
	v_mov_b64_e32 v[86:87], 0
	v_mov_b64_e32 v[88:89], 0
	v_mov_b64_e32 v[90:91], 0
	v_mov_b64_e32 v[92:93], 0
	v_mov_b64_e32 v[94:95], 0
	v_mov_b64_e32 v[96:97], 0
	v_mov_b64_e32 v[98:99], 0
	v_mov_b64_e32 v[100:101], 0
	v_mov_b64_e32 v[102:103], 0
	v_mov_b64_e32 v[104:105], 0
	v_mov_b64_e32 v[106:107], 0
	v_mov_b64_e32 v[108:109], 0
	v_mov_b64_e32 v[110:111], 0
	v_mov_b64_e32 v[112:113], 0
	v_mov_b64_e32 v[114:115], 0
	v_mov_b64_e32 v[116:117], 0
	v_mov_b64_e32 v[118:119], 0
	v_mov_b64_e32 v[120:121], 0
	v_mov_b64_e32 v[122:123], 0
	v_mov_b64_e32 v[124:125], 0
	v_mov_b64_e32 v[126:127], 0
	s_cmp_eq_u32 s78, 1
	s_cbranch_scc0 .Lhalf_skip_y_5
	s_barrier

;     __host__ __device__ bool next(int i, Unit& u) const { const int j = i / 3; if (!StaticOrder::next(j, u)) return false; u.br = i - 3 * j; return true; }
; template <class Epi, class Sched>
; __device__ __forceinline__ void gemm_phase(PG8_LAS unsigned char* lds, const Gemm g, const Sched& S, const Epi& E) {
;     ...
;         const bool has_next = S.next(ui + 1, nxt);
;         const char* nA = has_next ? (const char*)g.A + (size_t)nxt.pm * tstep + (size_t)nxt.br * g.strideA : cA; const char* nB = has_next ? (const char*)g.Bt + (size_t)nxt.pn * tstepB + (size_t)nxt.br * g.strideB : cB;
;     ...
; #pragma unroll
;         for (int a = 0; a < 2; ++a)
; #pragma unroll
;             for (int b = 0; b < 2; ++b)
; #pragma unroll
;                 for (int m = 0; m < 4; ++m)
; #pragma unroll
;                     for (int n = 0; n < 2; ++n) acc[a][b][m][n] = (f32x4){0.f, 0.f, 0.f, 0.f};
.LBB0_903:
	s_ashr_i32 s11, s10, 31
	v_cmp_lt_i64_e32 vcc, s[14:15], v[140:141]
	s_lshl_b64 s[14:15], s[10:11], 20
	s_add_u32 s14, s29, s14
	s_addc_u32 s15, s30, s15
	s_and_b64 s[16:17], vcc, exec
	s_cselect_b32 s11, s15, s23
	s_cselect_b32 s57, s14, s22
	s_ashr_i32 s13, s12, 31
	s_lshl_b64 s[16:17], s[12:13], 20
	s_add_u32 s16, s31, s16
	s_addc_u32 s17, s36, s17
	s_and_b64 s[24:25], vcc, exec
	s_cselect_b32 s13, s17, s21
	s_cselect_b32 s58, s16, s20
	s_add_u32 s59, s20, 0x10000
	s_addc_u32 s60, s21, 0
	s_add_u32 s20, s22, 0x80080
	v_mov_b32_e32 v0, 0
	s_addc_u32 s21, s23, 0
	s_mov_b32 s61, -2
	v_mov_b32_e32 v1, v0
	v_mov_b64_e32 v[2:3], 0
	v_mov_b64_e32 v[4:5], 0
	v_mov_b64_e32 v[6:7], 0
	v_mov_b64_e32 v[8:9], 0
	v_mov_b64_e32 v[10:11], 0
	v_mov_b64_e32 v[12:13], 0
	v_mov_b64_e32 v[14:15], 0
	v_mov_b64_e32 v[16:17], 0
	v_mov_b64_e32 v[18:19], 0
	v_mov_b64_e32 v[20:21], 0
	v_mov_b64_e32 v[22:23], 0
	v_mov_b64_e32 v[24:25], 0
	v_mov_b64_e32 v[26:27], 0
	v_mov_b64_e32 v[28:29], 0
	v_mov_b64_e32 v[30:31], 0
	v_mov_b64_e32 v[32:33], 0
	v_mov_b64_e32 v[34:35], 0
	v_mov_b64_e32 v[36:37], 0
	v_mov_b64_e32 v[38:39], 0
	v_mov_b64_e32 v[40:41], 0
	v_mov_b64_e32 v[42:43], 0
	v_mov_b64_e32 v[44:45], 0
	v_mov_b64_e32 v[46:47], 0
	v_mov_b64_e32 v[48:49], 0
	v_mov_b64_e32 v[50:51], 0
	v_mov_b64_e32 v[52:53], 0
	v_mov_b64_e32 v[54:55], 0
	v_mov_b64_e32 v[56:57], 0
	v_mov_b64_e32 v[58:59], 0
	v_mov_b64_e32 v[60:61], 0
	v_mov_b64_e32 v[62:63], 0
	v_mov_b64_e32 v[64:65], 0
	v_mov_b64_e32 v[66:67], 0
	v_mov_b64_e32 v[68:69], 0
	v_mov_b64_e32 v[70:71], 0
	v_mov_b64_e32 v[72:73], 0
	v_mov_b64_e32 v[74:75], 0
	v_mov_b64_e32 v[76:77], 0
	v_mov_b64_e32 v[78:79], 0
	v_mov_b64_e32 v[80:81], 0
	v_mov_b64_e32 v[82:83], 0
	v_mov_b64_e32 v[84:85], 0
	v_mov_b64_e32 v[86:87], 0
	v_mov_b64_e32 v[88:89], 0
	v_mov_b64_e32 v[90:91], 0
	v_mov_b64_e32 v[92:93], 0
	v_mov_b64_e32 v[94:95], 0
	v_mov_b64_e32 v[96:97], 0
	v_mov_b64_e32 v[98:99], 0
	v_mov_b64_e32 v[100:101], 0
	v_mov_b64_e32 v[102:103], 0
	v_mov_b64_e32 v[104:105], 0
	v_mov_b64_e32 v[106:107], 0
	v_mov_b64_e32 v[108:109], 0
	v_mov_b64_e32 v[110:111], 0
	v_mov_b64_e32 v[112:113], 0
	v_mov_b64_e32 v[114:115], 0
	v_mov_b64_e32 v[116:117], 0
	v_mov_b64_e32 v[118:119], 0
	v_mov_b64_e32 v[120:121], 0
	v_mov_b64_e32 v[122:123], 0
	v_mov_b64_e32 v[124:125], 0
	v_mov_b64_e32 v[126:127], 0
	s_cmp_eq_u32 s78, 1
	s_cbranch_scc0 .Lhalf_skip_y_6
	s_barrier

; template <class Epi, class Sched>
; __device__ __forceinline__ void gemm_phase(PG8_LAS unsigned char* lds, const Gemm g, const Sched& S, const Epi& E) {
;     ...
; #pragma unroll
;         for (int a = 0; a < 2; ++a)
; #pragma unroll
;             for (int b = 0; b < 2; ++b)
; #pragma unroll
;                 for (int m = 0; m < 4; ++m)
; #pragma unroll
;                     for (int n = 0; n < 2; ++n) acc[a][b][m][n] = (f32x4){0.f, 0.f, 0.f, 0.f};
.LBB0_979:
	s_add_u32 s63, s24, 0x10000
	v_mov_b32_e32 v0, 0
	s_addc_u32 s64, s25, 0
	s_mov_b32 s65, -2
	v_mov_b32_e32 v1, v0
	v_mov_b64_e32 v[2:3], 0
	v_mov_b64_e32 v[4:5], 0
	v_mov_b64_e32 v[6:7], 0
	v_mov_b64_e32 v[8:9], 0
	v_mov_b64_e32 v[10:11], 0
	v_mov_b64_e32 v[12:13], 0
	v_mov_b64_e32 v[14:15], 0
	v_mov_b64_e32 v[16:17], 0
	v_mov_b64_e32 v[18:19], 0
	v_mov_b64_e32 v[20:21], 0
	v_mov_b64_e32 v[22:23], 0
	v_mov_b64_e32 v[24:25], 0
	v_mov_b64_e32 v[26:27], 0
	v_mov_b64_e32 v[28:29], 0
	v_mov_b64_e32 v[30:31], 0
	v_mov_b64_e32 v[32:33], 0
	v_mov_b64_e32 v[34:35], 0
	v_mov_b64_e32 v[36:37], 0
	v_mov_b64_e32 v[38:39], 0
	v_mov_b64_e32 v[40:41], 0
	v_mov_b64_e32 v[42:43], 0
	v_mov_b64_e32 v[44:45], 0
	v_mov_b64_e32 v[46:47], 0
	v_mov_b64_e32 v[48:49], 0
	v_mov_b64_e32 v[50:51], 0
	v_mov_b64_e32 v[52:53], 0
	v_mov_b64_e32 v[54:55], 0
	v_mov_b64_e32 v[56:57], 0
	v_mov_b64_e32 v[58:59], 0
	v_mov_b64_e32 v[60:61], 0
	v_mov_b64_e32 v[62:63], 0
	v_mov_b64_e32 v[64:65], 0
	v_mov_b64_e32 v[66:67], 0
	v_mov_b64_e32 v[68:69], 0
	v_mov_b64_e32 v[70:71], 0
	v_mov_b64_e32 v[72:73], 0
	v_mov_b64_e32 v[74:75], 0
	v_mov_b64_e32 v[76:77], 0
	v_mov_b64_e32 v[78:79], 0
	v_mov_b64_e32 v[80:81], 0
	v_mov_b64_e32 v[82:83], 0
	v_mov_b64_e32 v[84:85], 0
	v_mov_b64_e32 v[86:87], 0
	v_mov_b64_e32 v[88:89], 0
	v_mov_b64_e32 v[90:91], 0
	v_mov_b64_e32 v[92:93], 0
	v_mov_b64_e32 v[94:95], 0
	v_mov_b64_e32 v[96:97], 0
	v_mov_b64_e32 v[98:99], 0
	v_mov_b64_e32 v[100:101], 0
	v_mov_b64_e32 v[102:103], 0
	v_mov_b64_e32 v[104:105], 0
	v_mov_b64_e32 v[106:107], 0
	v_mov_b64_e32 v[108:109], 0
	v_mov_b64_e32 v[110:111], 0
	v_mov_b64_e32 v[112:113], 0
	v_mov_b64_e32 v[114:115], 0
	v_mov_b64_e32 v[116:117], 0
	v_mov_b64_e32 v[118:119], 0
	v_mov_b64_e32 v[120:121], 0
	v_mov_b64_e32 v[122:123], 0
	v_mov_b64_e32 v[124:125], 0
	v_mov_b64_e32 v[126:127], 0
	s_cmp_eq_u32 s78, 1
	s_cbranch_scc0 .Lhalf_skip_y_7
	s_barrier
